# FIX phase: 16 loads issued together, one wait, eight add+store steps
# speedup vs baseline: 1.2515x; 1.0021x over previous
; __device__ __forceinline__ float bflo(unsigned u) { return __uint_as_float(u << 16); }
; __device__ __forceinline__ float bfhi(unsigned u) { return __uint_as_float(u & 0xffff0000u); }
; __device__ __forceinline__ void phase4a_fixup(const Params& p) {
;   const int tid = threadIdx.x;
;   char* ws = p.ws;
;   const int NG = 132 * 8, G = (int)gridDim.x;
;   const int nfull = NG / G, nleft = NG - nfull * G;
;   const bool split_ok = (2 * nleft <= G) && (nleft <= P4A_MAX_LEFT);
;   if (!split_ok || (int)blockIdx.x >= nleft) return;
;   const int it = nfull * G + (int)blockIdx.x;
;   const int nt = it & 7, mt = it >> 3;
;   u16* MRG = (u16*)(ws + OFF_MRG) + (size_t)mt * 128 * 1024 + nt * 128;
;   const u16* MRG2 = (const u16*)(ws + OFF_MRG2) + (size_t)blockIdx.x * 16384;
; #pragma unroll
;   for (int q = 0; q < 8; q++) {
;     const int idx = tid + 256 * q, row = idx >> 4, c8 = idx & 15;
;     u16* mp = MRG + (size_t)row * 1024 + c8 * 8;
;     uint4 v4 = *(const uint4*)mp;
;     const uint4 o4 = *(const uint4*)(MRG2 + row * 128 + c8 * 8);
;     v4.x = pack2(bflo(v4.x) + bflo(o4.x), bfhi(v4.x) + bfhi(o4.x));
;     v4.y = pack2(bflo(v4.y) + bflo(o4.y), bfhi(v4.y) + bfhi(o4.y));
;     v4.z = pack2(bflo(v4.z) + bflo(o4.z), bfhi(v4.z) + bfhi(o4.z));
;     v4.w = pack2(bflo(v4.w) + bflo(o4.w), bfhi(v4.w) + bfhi(o4.w));
;     *(uint4*)mp = v4;
;   }
; }
.LBB0_1234:
	s_or_b64 exec, exec, s[0:1]
	s_cmp_gt_u32 s55, 64
	s_cselect_b64 s[0:1], -1, 0
	s_xor_b64 s[2:3], s[2:3], -1
	s_or_b64 s[0:1], s[2:3], s[0:1]
	s_cmp_ge_i32 s96, s55
	s_cselect_b64 s[2:3], -1, 0
	s_or_b64 s[0:1], s[2:3], s[0:1]
	s_and_b64 vcc, exec, s[0:1]
	s_waitcnt lgkmcnt(0)
	s_barrier
	s_cbranch_vccnz .LBB0_1236
	s_sub_i32 s2, s96, s55
	s_add_i32 s0, s2, 0x420
	s_ashr_i32 s0, s0, 3
	s_ashr_i32 s1, s0, 31
	s_lshl_b64 s[0:1], s[0:1], 18
	s_add_u32 s0, s33, s0
	s_addc_u32 s1, s54, s1
	s_lshl_b32 s2, s2, 8
	s_and_b32 s2, s2, 0x700
	s_mov_b32 s97, 0
	s_add_u32 s0, s0, s2
	s_addc_u32 s1, s1, 0
	s_lshl_b64 s[2:3], s[96:97], 15
	s_add_u32 s2, s75, s2
	v_accvgpr_read_b32 v0, a138
	s_addc_u32 s3, s86, s3
	v_and_b32_e32 v0, 0xf0, v0
	v_mov_b32_e32 v1, 0
	v_accvgpr_read_b32 v28, a126
	v_lshl_add_u64 v[4:5], s[0:1], 0, v[0:1]
	v_lshl_add_u64 v[2:3], s[2:3], 0, v[0:1]
	v_lshlrev_b32_e32 v0, 11, v28
	v_lshl_add_u64 v[14:15], v[4:5], 0, v[0:1]
	v_lshlrev_b32_e32 v0, 8, v28
	v_lshl_add_u64 v[10:11], v[2:3], 0, v[0:1]
	s_mov_b32 s99, 0
	s_mov_b32 s98, 0x0
	v_lshl_add_u64 v[30:31], v[14:15], 0, s[98:99]
	global_load_dwordx4 a[196:199], v[30:31], off
	s_mov_b32 s98, 0x0
	v_lshl_add_u64 v[28:29], v[10:11], 0, s[98:99]
	global_load_dwordx4 v[32:35], v[28:29], off
	s_mov_b32 s98, 0x8000
	v_lshl_add_u64 v[30:31], v[14:15], 0, s[98:99]
	global_load_dwordx4 a[200:203], v[30:31], off
	s_mov_b32 s98, 0x1000
	v_lshl_add_u64 v[28:29], v[10:11], 0, s[98:99]
	global_load_dwordx4 v[36:39], v[28:29], off
	s_mov_b32 s98, 0x10000
	v_lshl_add_u64 v[30:31], v[14:15], 0, s[98:99]
	global_load_dwordx4 a[204:207], v[30:31], off
	s_mov_b32 s98, 0x2000
	v_lshl_add_u64 v[28:29], v[10:11], 0, s[98:99]
	global_load_dwordx4 v[40:43], v[28:29], off
	s_mov_b32 s98, 0x18000
	v_lshl_add_u64 v[30:31], v[14:15], 0, s[98:99]
	global_load_dwordx4 a[208:211], v[30:31], off
	s_mov_b32 s98, 0x3000
	v_lshl_add_u64 v[28:29], v[10:11], 0, s[98:99]
	global_load_dwordx4 v[44:47], v[28:29], off
	s_mov_b32 s98, 0x20000
	v_lshl_add_u64 v[30:31], v[14:15], 0, s[98:99]
	global_load_dwordx4 a[212:215], v[30:31], off
	s_mov_b32 s98, 0x4000
	v_lshl_add_u64 v[28:29], v[10:11], 0, s[98:99]
	global_load_dwordx4 v[48:51], v[28:29], off
	s_mov_b32 s98, 0x28000
	v_lshl_add_u64 v[30:31], v[14:15], 0, s[98:99]
	global_load_dwordx4 a[216:219], v[30:31], off
	s_mov_b32 s98, 0x5000
	v_lshl_add_u64 v[28:29], v[10:11], 0, s[98:99]
	global_load_dwordx4 v[52:55], v[28:29], off
	s_mov_b32 s98, 0x30000
	v_lshl_add_u64 v[30:31], v[14:15], 0, s[98:99]
	global_load_dwordx4 a[220:223], v[30:31], off
	s_mov_b32 s98, 0x6000
	v_lshl_add_u64 v[28:29], v[10:11], 0, s[98:99]
	global_load_dwordx4 v[56:59], v[28:29], off
	s_mov_b32 s98, 0x38000
	v_lshl_add_u64 v[30:31], v[14:15], 0, s[98:99]
	global_load_dwordx4 a[224:227], v[30:31], off
	s_mov_b32 s98, 0x7000
	v_lshl_add_u64 v[28:29], v[10:11], 0, s[98:99]
	global_load_dwordx4 v[60:63], v[28:29], off
	s_waitcnt vmcnt(0)
	v_accvgpr_read_b32 v6, a196
	v_lshlrev_b32_e32 v22, 16, v32
	v_and_b32_e32 v23, 0xffff0000, v32
	v_lshlrev_b32_e32 v20, 16, v6
	v_and_b32_e32 v21, 0xffff0000, v6
	v_pk_add_f32 v[20:21], v[20:21], v[22:23]
	s_nop 0
	v_cvt_pk_bf16_f32 v24, v20, v21
	v_accvgpr_read_b32 v6, a197
	v_lshlrev_b32_e32 v22, 16, v33
	v_and_b32_e32 v23, 0xffff0000, v33
	v_lshlrev_b32_e32 v20, 16, v6
	v_and_b32_e32 v21, 0xffff0000, v6
	v_pk_add_f32 v[20:21], v[20:21], v[22:23]
	s_nop 0
	v_cvt_pk_bf16_f32 v25, v20, v21
	v_accvgpr_read_b32 v6, a198
	v_lshlrev_b32_e32 v22, 16, v34
	v_and_b32_e32 v23, 0xffff0000, v34
	v_lshlrev_b32_e32 v20, 16, v6
	v_and_b32_e32 v21, 0xffff0000, v6
	v_pk_add_f32 v[20:21], v[20:21], v[22:23]
	s_nop 0
	v_cvt_pk_bf16_f32 v26, v20, v21
	v_accvgpr_read_b32 v6, a199
	v_lshlrev_b32_e32 v22, 16, v35
	v_and_b32_e32 v23, 0xffff0000, v35
	v_lshlrev_b32_e32 v20, 16, v6
	v_and_b32_e32 v21, 0xffff0000, v6
	v_pk_add_f32 v[20:21], v[20:21], v[22:23]
	s_nop 0
	v_cvt_pk_bf16_f32 v27, v20, v21
	s_mov_b32 s98, 0x0
	v_lshl_add_u64 v[30:31], v[14:15], 0, s[98:99]
	global_store_dwordx4 v[30:31], v[24:27], off
	v_accvgpr_read_b32 v6, a200
	v_lshlrev_b32_e32 v22, 16, v36
	v_and_b32_e32 v23, 0xffff0000, v36
	v_lshlrev_b32_e32 v20, 16, v6
	v_and_b32_e32 v21, 0xffff0000, v6
	v_pk_add_f32 v[20:21], v[20:21], v[22:23]
	s_nop 0
	v_cvt_pk_bf16_f32 v24, v20, v21
	v_accvgpr_read_b32 v6, a201
	v_lshlrev_b32_e32 v22, 16, v37
	v_and_b32_e32 v23, 0xffff0000, v37
	v_lshlrev_b32_e32 v20, 16, v6
	v_and_b32_e32 v21, 0xffff0000, v6
	v_pk_add_f32 v[20:21], v[20:21], v[22:23]
	s_nop 0
	v_cvt_pk_bf16_f32 v25, v20, v21
	v_accvgpr_read_b32 v6, a202
	v_lshlrev_b32_e32 v22, 16, v38
	v_and_b32_e32 v23, 0xffff0000, v38
	v_lshlrev_b32_e32 v20, 16, v6
	v_and_b32_e32 v21, 0xffff0000, v6
	v_pk_add_f32 v[20:21], v[20:21], v[22:23]
	s_nop 0
	v_cvt_pk_bf16_f32 v26, v20, v21
	v_accvgpr_read_b32 v6, a203
	v_lshlrev_b32_e32 v22, 16, v39
	v_and_b32_e32 v23, 0xffff0000, v39
	v_lshlrev_b32_e32 v20, 16, v6
	v_and_b32_e32 v21, 0xffff0000, v6
	v_pk_add_f32 v[20:21], v[20:21], v[22:23]
	s_nop 0
	v_cvt_pk_bf16_f32 v27, v20, v21
	s_mov_b32 s98, 0x8000
	v_lshl_add_u64 v[30:31], v[14:15], 0, s[98:99]
	global_store_dwordx4 v[30:31], v[24:27], off
	v_accvgpr_read_b32 v6, a204
	v_lshlrev_b32_e32 v22, 16, v40
	v_and_b32_e32 v23, 0xffff0000, v40
	v_lshlrev_b32_e32 v20, 16, v6
	v_and_b32_e32 v21, 0xffff0000, v6
	v_pk_add_f32 v[20:21], v[20:21], v[22:23]
	s_nop 0
	v_cvt_pk_bf16_f32 v24, v20, v21
	v_accvgpr_read_b32 v6, a205
	v_lshlrev_b32_e32 v22, 16, v41
	v_and_b32_e32 v23, 0xffff0000, v41
	v_lshlrev_b32_e32 v20, 16, v6
	v_and_b32_e32 v21, 0xffff0000, v6
	v_pk_add_f32 v[20:21], v[20:21], v[22:23]
	s_nop 0
	v_cvt_pk_bf16_f32 v25, v20, v21
; __device__ __forceinline__ float bflo(unsigned u) { return __uint_as_float(u << 16); }
; __device__ __forceinline__ float bfhi(unsigned u) { return __uint_as_float(u & 0xffff0000u); }
; __device__ __forceinline__ void phase4a_fixup(const Params& p) {
;     ...
; #pragma unroll
;   for (int q = 0; q < 8; q++) {
;     const int idx = tid + 256 * q, row = idx >> 4, c8 = idx & 15;
;     u16* mp = MRG + (size_t)row * 1024 + c8 * 8;
;     uint4 v4 = *(const uint4*)mp;
;     const uint4 o4 = *(const uint4*)(MRG2 + row * 128 + c8 * 8);
;     v4.x = pack2(bflo(v4.x) + bflo(o4.x), bfhi(v4.x) + bfhi(o4.x));
;     v4.y = pack2(bflo(v4.y) + bflo(o4.y), bfhi(v4.y) + bfhi(o4.y));
;     v4.z = pack2(bflo(v4.z) + bflo(o4.z), bfhi(v4.z) + bfhi(o4.z));
;     v4.w = pack2(bflo(v4.w) + bflo(o4.w), bfhi(v4.w) + bfhi(o4.w));
;     *(uint4*)mp = v4;
;   }
	v_accvgpr_read_b32 v6, a206
	v_lshlrev_b32_e32 v22, 16, v42
	v_and_b32_e32 v23, 0xffff0000, v42
	v_lshlrev_b32_e32 v20, 16, v6
	v_and_b32_e32 v21, 0xffff0000, v6
	v_pk_add_f32 v[20:21], v[20:21], v[22:23]
	s_nop 0
	v_cvt_pk_bf16_f32 v26, v20, v21
	v_accvgpr_read_b32 v6, a207
	v_lshlrev_b32_e32 v22, 16, v43
	v_and_b32_e32 v23, 0xffff0000, v43
	v_lshlrev_b32_e32 v20, 16, v6
	v_and_b32_e32 v21, 0xffff0000, v6
	v_pk_add_f32 v[20:21], v[20:21], v[22:23]
	s_nop 0
	v_cvt_pk_bf16_f32 v27, v20, v21
	s_mov_b32 s98, 0x10000
	v_lshl_add_u64 v[30:31], v[14:15], 0, s[98:99]
	global_store_dwordx4 v[30:31], v[24:27], off
	v_accvgpr_read_b32 v6, a208
	v_lshlrev_b32_e32 v22, 16, v44
	v_and_b32_e32 v23, 0xffff0000, v44
	v_lshlrev_b32_e32 v20, 16, v6
	v_and_b32_e32 v21, 0xffff0000, v6
	v_pk_add_f32 v[20:21], v[20:21], v[22:23]
	s_nop 0
	v_cvt_pk_bf16_f32 v24, v20, v21
	v_accvgpr_read_b32 v6, a209
	v_lshlrev_b32_e32 v22, 16, v45
	v_and_b32_e32 v23, 0xffff0000, v45
	v_lshlrev_b32_e32 v20, 16, v6
	v_and_b32_e32 v21, 0xffff0000, v6
	v_pk_add_f32 v[20:21], v[20:21], v[22:23]
	s_nop 0
	v_cvt_pk_bf16_f32 v25, v20, v21
	v_accvgpr_read_b32 v6, a210
	v_lshlrev_b32_e32 v22, 16, v46
	v_and_b32_e32 v23, 0xffff0000, v46
	v_lshlrev_b32_e32 v20, 16, v6
	v_and_b32_e32 v21, 0xffff0000, v6
	v_pk_add_f32 v[20:21], v[20:21], v[22:23]
	s_nop 0
	v_cvt_pk_bf16_f32 v26, v20, v21
	v_accvgpr_read_b32 v6, a211
	v_lshlrev_b32_e32 v22, 16, v47
	v_and_b32_e32 v23, 0xffff0000, v47
	v_lshlrev_b32_e32 v20, 16, v6
	v_and_b32_e32 v21, 0xffff0000, v6
	v_pk_add_f32 v[20:21], v[20:21], v[22:23]
	s_nop 0
	v_cvt_pk_bf16_f32 v27, v20, v21
	s_mov_b32 s98, 0x18000
	v_lshl_add_u64 v[30:31], v[14:15], 0, s[98:99]
	global_store_dwordx4 v[30:31], v[24:27], off
	v_accvgpr_read_b32 v6, a212
	v_lshlrev_b32_e32 v22, 16, v48
	v_and_b32_e32 v23, 0xffff0000, v48
	v_lshlrev_b32_e32 v20, 16, v6
	v_and_b32_e32 v21, 0xffff0000, v6
	v_pk_add_f32 v[20:21], v[20:21], v[22:23]
	s_nop 0
	v_cvt_pk_bf16_f32 v24, v20, v21
	v_accvgpr_read_b32 v6, a213
	v_lshlrev_b32_e32 v22, 16, v49
	v_and_b32_e32 v23, 0xffff0000, v49
	v_lshlrev_b32_e32 v20, 16, v6
	v_and_b32_e32 v21, 0xffff0000, v6
	v_pk_add_f32 v[20:21], v[20:21], v[22:23]
	s_nop 0
	v_cvt_pk_bf16_f32 v25, v20, v21
	v_accvgpr_read_b32 v6, a214
	v_lshlrev_b32_e32 v22, 16, v50
	v_and_b32_e32 v23, 0xffff0000, v50
	v_lshlrev_b32_e32 v20, 16, v6
	v_and_b32_e32 v21, 0xffff0000, v6
	v_pk_add_f32 v[20:21], v[20:21], v[22:23]
	s_nop 0
	v_cvt_pk_bf16_f32 v26, v20, v21
	v_accvgpr_read_b32 v6, a215
	v_lshlrev_b32_e32 v22, 16, v51
	v_and_b32_e32 v23, 0xffff0000, v51
	v_lshlrev_b32_e32 v20, 16, v6
	v_and_b32_e32 v21, 0xffff0000, v6
	v_pk_add_f32 v[20:21], v[20:21], v[22:23]
	s_nop 0
	v_cvt_pk_bf16_f32 v27, v20, v21
	s_mov_b32 s98, 0x20000
	v_lshl_add_u64 v[30:31], v[14:15], 0, s[98:99]
	global_store_dwordx4 v[30:31], v[24:27], off
	v_accvgpr_read_b32 v6, a216
	v_lshlrev_b32_e32 v22, 16, v52
	v_and_b32_e32 v23, 0xffff0000, v52
	v_lshlrev_b32_e32 v20, 16, v6
	v_and_b32_e32 v21, 0xffff0000, v6
	v_pk_add_f32 v[20:21], v[20:21], v[22:23]
	s_nop 0
	v_cvt_pk_bf16_f32 v24, v20, v21
	v_accvgpr_read_b32 v6, a217
	v_lshlrev_b32_e32 v22, 16, v53
	v_and_b32_e32 v23, 0xffff0000, v53
	v_lshlrev_b32_e32 v20, 16, v6
	v_and_b32_e32 v21, 0xffff0000, v6
	v_pk_add_f32 v[20:21], v[20:21], v[22:23]
	s_nop 0
	v_cvt_pk_bf16_f32 v25, v20, v21
	v_accvgpr_read_b32 v6, a218
	v_lshlrev_b32_e32 v22, 16, v54
	v_and_b32_e32 v23, 0xffff0000, v54
	v_lshlrev_b32_e32 v20, 16, v6
	v_and_b32_e32 v21, 0xffff0000, v6
	v_pk_add_f32 v[20:21], v[20:21], v[22:23]
	s_nop 0
	v_cvt_pk_bf16_f32 v26, v20, v21
	v_accvgpr_read_b32 v6, a219
	v_lshlrev_b32_e32 v22, 16, v55
	v_and_b32_e32 v23, 0xffff0000, v55
	v_lshlrev_b32_e32 v20, 16, v6
	v_and_b32_e32 v21, 0xffff0000, v6
	v_pk_add_f32 v[20:21], v[20:21], v[22:23]
	s_nop 0
	v_cvt_pk_bf16_f32 v27, v20, v21
	s_mov_b32 s98, 0x28000
	v_lshl_add_u64 v[30:31], v[14:15], 0, s[98:99]
	global_store_dwordx4 v[30:31], v[24:27], off
	v_accvgpr_read_b32 v6, a220
	v_lshlrev_b32_e32 v22, 16, v56
	v_and_b32_e32 v23, 0xffff0000, v56
	v_lshlrev_b32_e32 v20, 16, v6
	v_and_b32_e32 v21, 0xffff0000, v6
	v_pk_add_f32 v[20:21], v[20:21], v[22:23]
	s_nop 0
	v_cvt_pk_bf16_f32 v24, v20, v21
	v_accvgpr_read_b32 v6, a221
	v_lshlrev_b32_e32 v22, 16, v57
	v_and_b32_e32 v23, 0xffff0000, v57
	v_lshlrev_b32_e32 v20, 16, v6
	v_and_b32_e32 v21, 0xffff0000, v6
	v_pk_add_f32 v[20:21], v[20:21], v[22:23]
	s_nop 0
	v_cvt_pk_bf16_f32 v25, v20, v21
	v_accvgpr_read_b32 v6, a222
	v_lshlrev_b32_e32 v22, 16, v58
	v_and_b32_e32 v23, 0xffff0000, v58
	v_lshlrev_b32_e32 v20, 16, v6
	v_and_b32_e32 v21, 0xffff0000, v6
	v_pk_add_f32 v[20:21], v[20:21], v[22:23]
	s_nop 0
	v_cvt_pk_bf16_f32 v26, v20, v21
	v_accvgpr_read_b32 v6, a223
	v_lshlrev_b32_e32 v22, 16, v59
	v_and_b32_e32 v23, 0xffff0000, v59
	v_lshlrev_b32_e32 v20, 16, v6
	v_and_b32_e32 v21, 0xffff0000, v6
	v_pk_add_f32 v[20:21], v[20:21], v[22:23]
	s_nop 0
	v_cvt_pk_bf16_f32 v27, v20, v21
	s_mov_b32 s98, 0x30000
	v_lshl_add_u64 v[30:31], v[14:15], 0, s[98:99]
	global_store_dwordx4 v[30:31], v[24:27], off
	v_accvgpr_read_b32 v6, a224
	v_lshlrev_b32_e32 v22, 16, v60
	v_and_b32_e32 v23, 0xffff0000, v60
	v_lshlrev_b32_e32 v20, 16, v6
	v_and_b32_e32 v21, 0xffff0000, v6
	v_pk_add_f32 v[20:21], v[20:21], v[22:23]
	s_nop 0
	v_cvt_pk_bf16_f32 v24, v20, v21
	v_accvgpr_read_b32 v6, a225
	v_lshlrev_b32_e32 v22, 16, v61
	v_and_b32_e32 v23, 0xffff0000, v61
	v_lshlrev_b32_e32 v20, 16, v6
	v_and_b32_e32 v21, 0xffff0000, v6
	v_pk_add_f32 v[20:21], v[20:21], v[22:23]
	s_nop 0
	v_cvt_pk_bf16_f32 v25, v20, v21
	v_accvgpr_read_b32 v6, a226
	v_lshlrev_b32_e32 v22, 16, v62
	v_and_b32_e32 v23, 0xffff0000, v62
	v_lshlrev_b32_e32 v20, 16, v6
	v_and_b32_e32 v21, 0xffff0000, v6
	v_pk_add_f32 v[20:21], v[20:21], v[22:23]
	s_nop 0
	v_cvt_pk_bf16_f32 v26, v20, v21
	v_accvgpr_read_b32 v6, a227
	v_lshlrev_b32_e32 v22, 16, v63
	v_and_b32_e32 v23, 0xffff0000, v63
	v_lshlrev_b32_e32 v20, 16, v6
	v_and_b32_e32 v21, 0xffff0000, v6
	v_pk_add_f32 v[20:21], v[20:21], v[22:23]
	s_nop 0
	v_cvt_pk_bf16_f32 v27, v20, v21
	s_mov_b32 s98, 0x38000
	v_lshl_add_u64 v[30:31], v[14:15], 0, s[98:99]
	global_store_dwordx4 v[30:31], v[24:27], off
